# gate-up next-tile arithmetic in the peeled load segments: division by the group height (8) as shift/mask too (removes 4 VALU + readfirstlane + 22 SALU from load segments 3 and 4)
# speedup vs baseline: 1.0179x; 1.0179x over previous
; #define PG8_STAGE(bufoff, gbase, voff) do { _Pragma("unroll") for (int _i = 0; _i < 2; ++_i) { \
;         const unsigned _m0 = ldsb + (unsigned)((bufoff) + _i * 8192); const char* _gb = (const char*)(gbase); \
;         asm volatile("s_mov_b32 m0, %0\n\ts_nop 0\n\tglobal_load_lds_dwordx4 %1, %2" :: "s"(_m0), "v"((voff)[_i]), "s"(_gb) : "m0", "memory"); } } while (0)
; #define PG8_LDA(dst, b, h) do { _Pragma("unroll") for (int m = 0; m < 4; ++m) _Pragma("unroll") for (int k = 0; k < 2; ++k) dst[m][k] = *(const LAS bf16x8*)(lds + PG8_SA(b, h) + aoff + m * 2048 + k * 1024); } while (0)
; #define PG8_LDB(dst, b, h) do { _Pragma("unroll") for (int n = 0; n < 2; ++n) _Pragma("unroll") for (int k = 0; k < 2; ++k) dst[n][k] = *(const LAS bf16x8*)(lds + PG8_SB(b, h) + boff + n * 2048 + k * 1024); } while (0)
;     __device__ bool next(int i, Unit& u) const {
;         const long L = (long)i * G + c; if (L >= nwg) return false;
;         int wgid = (int)L; { const int q = nwg / NXCD, r = nwg % NXCD, xcd = wgid % NXCD, off = wgid / NXCD; wgid = (xcd < r ? xcd * (q + 1) : r * (q + 1) + (xcd - r) * q) + off; }
;         const int nig = WGM * nN, gid = wgid / nig, fm = gid * WGM, gsz = (nM - fm) < WGM ? (nM - fm) : WGM;
;         u.pm = fm + ((wgid % nig) % gsz); u.pn = (wgid % nig) / gsz; return true;
; template <class Epi, bool ALIGN_EPI>
; __device__ __forceinline__ void gemm_phase(LAS unsigned char* lds, const Gemm g, const StaticOrder& S, const Epi& E) {
;     ...
;         const bool has_next = S.next(ui + 1, nxt);
;         const char* nA = has_next ? (const char*)g.A + (size_t)nxt.pm * tstepA + (size_t)nxt.pn * g.a_pn_off * 2 + (size_t)(nxt.pm >> 4) * g.a_adj : cA; const char* nB = has_next ? (const char*)g.Bt + (size_t)nxt.pn * tstepB : cB;
;         for (int t = 0; t < nt; t += 2) {
;             const bool last = (t == nt - 2);
;             const char* a1 = cA + (size_t)(t + 1) * kstep;
;             const char* a2 = last ? nA : cA + (size_t)(t + 2) * kstep; const char* b2 = last ? nB : cB + (size_t)(t + 2) * kstep;
;             const char* a3 = a2 + kstep; const char* b3 = b2 + kstep;
;             PG8_LDB(B0, 0, 0); PG8_LDB(B1, 0, 1); PG8_SCHED; PG8_LDA(At, 0, 0); PG8_STAGE(PG8_SA(1, 1), a1 + hstepA, voffA);
;             PG8_WAIT_V(8); PG8_WAIT_L(0); PG8_BAR; PG8_MMA(0, 0, At, B0); PG8_MMA(0, 1, At, B1); PG8_BAR; PG8_SCHED;
.LBB0_305:
	s_add_u32 s41, s56, 0x100
	s_addc_u32 s49, s57, 0
	s_add_u32 s92, s58, 0x40080
	s_addc_u32 s93, s59, 0
	s_mov_b32 s50, -2
	s_add_u32 s30, s92, 0xfffc0080
	s_addc_u32 s31, s93, -1
	s_cmp_eq_u32 s50, 12
	s_cselect_b32 s60, s5, s30
	s_cselect_b32 s61, s4, s31
	s_cselect_b32 s58, s37, s41
	s_cselect_b32 s59, s35, s49
	s_add_u32 s56, s60, 0x80
	s_addc_u32 s57, s61, 0
	s_mov_b32 m0, s67
	s_nop 0
	global_load_lds_dwordx4 v0, s[92:93]
	s_nop 0
	s_mov_b32 m0, s65
	s_nop 0
	global_load_lds_dwordx4 v181, s[92:93]
	s_waitcnt vmcnt(8)
	s_waitcnt lgkmcnt(0)
	s_setprio 1
	s_barrier
	v_mfma_f32_16x16x32_bf16 v[142:145], v[74:77], v[162:165], 0
	v_mfma_f32_16x16x32_bf16 v[142:145], v[94:97], v[166:169], v[142:145]
	v_mfma_f32_16x16x32_bf16 v[138:141], v[114:117], v[162:165], 0
	v_mfma_f32_16x16x32_bf16 v[138:141], v[134:137], v[166:169], v[138:141]
	v_mfma_f32_16x16x32_bf16 v[130:133], v[146:149], v[162:165], 0
	v_mfma_f32_16x16x32_bf16 v[130:133], v[150:153], v[166:169], v[130:133]
	v_mfma_f32_16x16x32_bf16 v[126:129], v[154:157], v[162:165], 0
	v_mfma_f32_16x16x32_bf16 v[126:129], v[158:161], v[166:169], v[126:129]
	v_mfma_f32_16x16x32_bf16 v[106:109], v[154:157], v[170:173], 0
	v_mfma_f32_16x16x32_bf16 v[106:109], v[158:161], v[174:177], v[106:109]
	v_mfma_f32_16x16x32_bf16 v[110:113], v[146:149], v[170:173], 0
	v_mfma_f32_16x16x32_bf16 v[110:113], v[150:153], v[174:177], v[110:113]
	v_mfma_f32_16x16x32_bf16 v[118:121], v[114:117], v[170:173], 0
	v_mfma_f32_16x16x32_bf16 v[118:121], v[134:137], v[174:177], v[118:121]
	v_mfma_f32_16x16x32_bf16 v[122:125], v[74:77], v[170:173], 0
	v_mfma_f32_16x16x32_bf16 v[122:125], v[94:97], v[174:177], v[122:125]
	v_mfma_f32_16x16x32_bf16 v[102:105], v[74:77], v[188:191], 0
	v_mfma_f32_16x16x32_bf16 v[102:105], v[94:97], v[202:205], v[102:105]
	v_mfma_f32_16x16x32_bf16 v[98:101], v[114:117], v[188:191], 0
	v_mfma_f32_16x16x32_bf16 v[98:101], v[134:137], v[202:205], v[98:101]
	v_mfma_f32_16x16x32_bf16 v[90:93], v[146:149], v[188:191], 0
	v_mfma_f32_16x16x32_bf16 v[90:93], v[150:153], v[202:205], v[90:93]
	v_mfma_f32_16x16x32_bf16 v[86:89], v[154:157], v[188:191], 0
	v_mfma_f32_16x16x32_bf16 v[86:89], v[158:161], v[202:205], v[86:89]
	v_mfma_f32_16x16x32_bf16 v[66:69], v[154:157], v[206:209], 0
	v_mfma_f32_16x16x32_bf16 v[66:69], v[158:161], v[210:213], v[66:69]
	v_mfma_f32_16x16x32_bf16 v[70:73], v[146:149], v[206:209], 0
	v_mfma_f32_16x16x32_bf16 v[70:73], v[150:153], v[210:213], v[70:73]
	v_mfma_f32_16x16x32_bf16 v[78:81], v[114:117], v[206:209], 0
	v_mfma_f32_16x16x32_bf16 v[78:81], v[134:137], v[210:213], v[78:81]
	v_mfma_f32_16x16x32_bf16 v[82:85], v[74:77], v[206:209], 0
	v_mfma_f32_16x16x32_bf16 v[82:85], v[94:97], v[210:213], v[82:85]
	s_barrier
	s_setprio 0
	v_mbcnt_lo_u32_b32 v178, -1, 0
	v_mbcnt_hi_u32_b32 v178, -1, v178
	s_lshl_b32 s90, s54, 8
	s_add_i32 s90, s90, s89
	s_lshl_b32 s91, s89, 4
	s_add_i32 s91, s91, 0x23000
	v_add_lshl_u32 v178, v178, s90, 4
	s_mov_b32 m0, s91
	s_nop 0
	global_load_lds_dwordx4 v178, s[24:25]
	global_load_lds_dwordx4 v178, s[24:25] offset:2048
	ds_read_b128 v[162:165], v186 offset:16384
	ds_read_b128 v[166:169], v186 offset:17408
	ds_read_b128 v[170:173], v186 offset:18432
	ds_read_b128 v[174:177], v186 offset:19456
	ds_read_b128 v[188:191], v186 offset:20480
	ds_read_b128 v[202:205], v186 offset:21504
	ds_read_b128 v[206:209], v186 offset:22528
	ds_read_b128 v[210:213], v186 offset:23552
	s_mov_b32 m0, s29
	s_nop 0
	global_load_lds_dwordx4 v180, s[58:59]
	s_add_u32 s30, s58, 0x40000
	s_mov_b32 m0, s42
	s_nop 0
	global_load_lds_dwordx4 v182, s[58:59]
	s_addc_u32 s31, s59, 0
	s_mov_b32 m0, s43
	s_nop 0
	global_load_lds_dwordx4 v180, s[30:31]
	s_nop 0
	s_mov_b32 m0, s44
	s_nop 0
	global_load_lds_dwordx4 v182, s[30:31]
	s_nop 0
	s_mov_b32 m0, s15
	s_nop 0
	global_load_lds_dwordx4 v0, s[60:61]
	s_nop 0
	s_mov_b32 m0, s45
	s_nop 0
	global_load_lds_dwordx4 v181, s[60:61]
	s_mul_i32 s4, s85, s27
	s_mul_hi_u32 s5, s85, s87
	s_add_i32 s5, s5, s4
	s_mul_i32 s4, s85, s87
	s_add_u32 s4, s4, s16
	s_addc_u32 s5, s5, s68
	v_mov_b64_e32 v[192:193], s[46:47]
	v_cmp_lt_i64_e64 s[8:9], s[4:5], v[192:193]
	s_ashr_i32 s5, s4, 31
	s_lshr_b32 s5, s5, 29
	s_add_i32 s5, s4, s5
	s_ashr_i32 s90, s5, 3
	s_and_b32 s5, s5, -8
	s_sub_i32 s4, s4, s5
	s_lshr_b32 s5, s4, 31
	s_or_b32 s5, s78, s5
	s_mul_i32 s4, s5, s4
	s_add_i32 s4, s4, s90
	s_abs_i32 s90, s4
	v_readlane_b32 s91, v254, 48
	s_mul_hi_u32 s91, s90, s91
	s_mul_i32 s34, s91, s26
	s_sub_i32 s90, s90, s34
	s_ashr_i32 s5, s4, 31
	s_add_i32 s34, s91, 1
	s_sub_i32 s35, s90, s26
	s_cmp_ge_u32 s90, s26
	s_cselect_b32 s91, s34, s91
	s_cselect_b32 s90, s35, s90
	s_waitcnt vmcnt(8)
	s_waitcnt lgkmcnt(0)
	s_setprio 1
	s_barrier
; #define PG8_STAGE(bufoff, gbase, voff) do { _Pragma("unroll") for (int _i = 0; _i < 2; ++_i) { \
;         const unsigned _m0 = ldsb + (unsigned)((bufoff) + _i * 8192); const char* _gb = (const char*)(gbase); \
;         asm volatile("s_mov_b32 m0, %0\n\ts_nop 0\n\tglobal_load_lds_dwordx4 %1, %2" :: "s"(_m0), "v"((voff)[_i]), "s"(_gb) : "m0", "memory"); } } while (0)
; #define PG8_LDA(dst, b, h) do { _Pragma("unroll") for (int m = 0; m < 4; ++m) _Pragma("unroll") for (int k = 0; k < 2; ++k) dst[m][k] = *(const LAS bf16x8*)(lds + PG8_SA(b, h) + aoff + m * 2048 + k * 1024); } while (0)
; #define PG8_MMA(ai, bj, At, Bt) do { __builtin_amdgcn_s_setprio(1); _Pragma("unroll") for (int m = 0; m < 4; ++m) _Pragma("unroll") for (int n = 0; n < 2; ++n) _Pragma("unroll") for (int k = 0; k < 2; ++k) \
;         acc[ai][bj][m][n] = __builtin_amdgcn_mfma_f32_16x16x32_bf16(Bt[n][k], At[m][k], acc[ai][bj][m][n], 0, 0, 0); __builtin_amdgcn_s_setprio(0); } while (0)
; #define PG8_WAIT_V(n) asm volatile("s_waitcnt vmcnt(" #n ")" ::: "memory")
; #define PG8_WAIT_L(n) asm volatile("s_waitcnt lgkmcnt(" #n ")" ::: "memory")
; #define PG8_BAR __builtin_amdgcn_s_barrier()
; #define PG8_SCHED __builtin_amdgcn_sched_barrier(0)
;     __device__ bool next(int i, Unit& u) const {
;     ...
;         const int nig = WGM * nN, gid = wgid / nig, fm = gid * WGM, gsz = (nM - fm) < WGM ? (nM - fm) : WGM;
;         u.pm = fm + ((wgid % nig) % gsz); u.pn = (wgid % nig) / gsz; return true;
; template <class Epi, bool ALIGN_EPI>
; __device__ __forceinline__ void gemm_phase(LAS unsigned char* lds, const Gemm g, const StaticOrder& S, const Epi& E) {
;     ...
;             PG8_WAIT_V(8); PG8_WAIT_L(0); PG8_BAR; PG8_MMA(0, 0, At, B0); PG8_MMA(0, 1, At, B1); PG8_BAR; PG8_SCHED;
;             PG8_LDA(At, 0, 1); PG8_STAGE(PG8_SB(0, 0), b2, voffB); PG8_STAGE(PG8_SB(0, 1), b2 + hstepB, voffB); PG8_STAGE(PG8_SA(0, 0), a2, voffA);
;             PG8_WAIT_V(8); PG8_WAIT_L(0); PG8_BAR; PG8_MMA(1, 0, At, B0); PG8_MMA(1, 1, At, B1); PG8_BAR; PG8_SCHED;
	v_mfma_f32_16x16x32_bf16 v[62:65], v[74:77], v[162:165], 0
	v_mfma_f32_16x16x32_bf16 v[62:65], v[94:97], v[166:169], v[62:65]
	v_mfma_f32_16x16x32_bf16 v[58:61], v[114:117], v[162:165], 0
	v_mfma_f32_16x16x32_bf16 v[58:61], v[134:137], v[166:169], v[58:61]
	v_mfma_f32_16x16x32_bf16 v[54:57], v[146:149], v[162:165], 0
	v_mfma_f32_16x16x32_bf16 v[54:57], v[150:153], v[166:169], v[54:57]
	v_mfma_f32_16x16x32_bf16 v[50:53], v[154:157], v[162:165], 0
	v_mfma_f32_16x16x32_bf16 v[50:53], v[158:161], v[166:169], v[50:53]
	v_mfma_f32_16x16x32_bf16 v[34:37], v[154:157], v[170:173], 0
	v_mfma_f32_16x16x32_bf16 v[34:37], v[158:161], v[174:177], v[34:37]
	v_mfma_f32_16x16x32_bf16 v[38:41], v[146:149], v[170:173], 0
	v_mfma_f32_16x16x32_bf16 v[38:41], v[150:153], v[174:177], v[38:41]
	v_mfma_f32_16x16x32_bf16 v[42:45], v[114:117], v[170:173], 0
	v_mfma_f32_16x16x32_bf16 v[42:45], v[134:137], v[174:177], v[42:45]
	v_mfma_f32_16x16x32_bf16 v[46:49], v[74:77], v[170:173], 0
	v_mfma_f32_16x16x32_bf16 v[46:49], v[94:97], v[174:177], v[46:49]
	v_mfma_f32_16x16x32_bf16 v[30:33], v[74:77], v[188:191], 0
	v_mfma_f32_16x16x32_bf16 v[30:33], v[94:97], v[202:205], v[30:33]
	v_mfma_f32_16x16x32_bf16 v[26:29], v[114:117], v[188:191], 0
	v_mfma_f32_16x16x32_bf16 v[26:29], v[134:137], v[202:205], v[26:29]
	v_mfma_f32_16x16x32_bf16 v[22:25], v[146:149], v[188:191], 0
	v_mfma_f32_16x16x32_bf16 v[22:25], v[150:153], v[202:205], v[22:25]
	v_mfma_f32_16x16x32_bf16 v[18:21], v[154:157], v[188:191], 0
	v_mfma_f32_16x16x32_bf16 v[18:21], v[158:161], v[202:205], v[18:21]
	v_mfma_f32_16x16x32_bf16 v[2:5], v[154:157], v[206:209], 0
	v_mfma_f32_16x16x32_bf16 v[2:5], v[158:161], v[210:213], v[2:5]
	v_mfma_f32_16x16x32_bf16 v[6:9], v[146:149], v[206:209], 0
	v_mfma_f32_16x16x32_bf16 v[6:9], v[150:153], v[210:213], v[6:9]
	v_mfma_f32_16x16x32_bf16 v[10:13], v[114:117], v[206:209], 0
	v_mfma_f32_16x16x32_bf16 v[10:13], v[134:137], v[210:213], v[10:13]
	v_mfma_f32_16x16x32_bf16 v[14:17], v[74:77], v[206:209], 0
	v_mfma_f32_16x16x32_bf16 v[14:17], v[94:97], v[210:213], v[14:17]
	s_barrier
	s_setprio 0
	v_add_u32_e32 v134, 0x18000, v185
	v_add_u32_e32 v158, 0x1c000, v185
	ds_read_b128 v[74:77], v134
	ds_read_b128 v[94:97], v134 offset:1024
	ds_read_b128 v[114:117], v134 offset:2048
	ds_read_b128 v[134:137], v134 offset:3072
	ds_read_b128 v[146:149], v158
	ds_read_b128 v[150:153], v158 offset:1024
	ds_read_b128 v[154:157], v158 offset:2048
	ds_read_b128 v[158:161], v158 offset:3072
	ds_read_b128 v[162:165], v186 offset:32768
	ds_read_b128 v[166:169], v186 offset:33792
	ds_read_b128 v[170:173], v186 offset:34816
	ds_read_b128 v[174:177], v186 offset:35840
	ds_read_b128 v[188:191], v186 offset:36864
	ds_read_b128 v[202:205], v186 offset:37888
	ds_read_b128 v[206:209], v186 offset:38912
	ds_read_b128 v[210:213], v186 offset:39936
	s_add_u32 s30, s60, 0x40000
	s_addc_u32 s31, s61, 0
	s_mov_b32 m0, s55
	s_nop 0
	global_load_lds_dwordx4 v0, s[30:31]
	s_nop 0
	s_mov_b32 m0, s88
	s_nop 0
	global_load_lds_dwordx4 v181, s[30:31]
	s_add_i32 s34, s91, 1
	s_cmp_ge_u32 s90, s26
	s_cselect_b32 s90, s34, s91
	s_xor_b32 s90, s90, s5
	s_sub_i32 s5, s90, s5
	s_lshl_b32 s90, s5, 3
	s_sub_i32 s91, 0x80, s90
	s_min_i32 s91, s91, 8
	s_mul_i32 s5, s5, s26
	s_sub_i32 s4, s4, s5
	s_lshr_b32 s34, s4, 3
	s_and_b32 s4, s4, 7
	s_waitcnt vmcnt(8)
	s_waitcnt lgkmcnt(0)
	s_setprio 1
	s_barrier
	v_mfma_f32_16x16x32_bf16 v[142:145], v[74:77], v[162:165], v[142:145]
	v_mfma_f32_16x16x32_bf16 v[142:145], v[94:97], v[166:169], v[142:145]
	v_mfma_f32_16x16x32_bf16 v[138:141], v[114:117], v[162:165], v[138:141]
	v_mfma_f32_16x16x32_bf16 v[138:141], v[134:137], v[166:169], v[138:141]
	v_mfma_f32_16x16x32_bf16 v[130:133], v[146:149], v[162:165], v[130:133]
	v_mfma_f32_16x16x32_bf16 v[130:133], v[150:153], v[166:169], v[130:133]
	v_mfma_f32_16x16x32_bf16 v[126:129], v[154:157], v[162:165], v[126:129]
	v_mfma_f32_16x16x32_bf16 v[126:129], v[158:161], v[166:169], v[126:129]
	v_mfma_f32_16x16x32_bf16 v[106:109], v[154:157], v[170:173], v[106:109]
	v_mfma_f32_16x16x32_bf16 v[106:109], v[158:161], v[174:177], v[106:109]
	v_mfma_f32_16x16x32_bf16 v[110:113], v[146:149], v[170:173], v[110:113]
	v_mfma_f32_16x16x32_bf16 v[110:113], v[150:153], v[174:177], v[110:113]
	v_mfma_f32_16x16x32_bf16 v[118:121], v[114:117], v[170:173], v[118:121]
	v_mfma_f32_16x16x32_bf16 v[118:121], v[134:137], v[174:177], v[118:121]
	v_mfma_f32_16x16x32_bf16 v[122:125], v[74:77], v[170:173], v[122:125]
	v_mfma_f32_16x16x32_bf16 v[122:125], v[94:97], v[174:177], v[122:125]
	v_mfma_f32_16x16x32_bf16 v[102:105], v[74:77], v[188:191], v[102:105]
	v_mfma_f32_16x16x32_bf16 v[102:105], v[94:97], v[202:205], v[102:105]
	v_mfma_f32_16x16x32_bf16 v[98:101], v[114:117], v[188:191], v[98:101]
	v_mfma_f32_16x16x32_bf16 v[98:101], v[134:137], v[202:205], v[98:101]
	v_mfma_f32_16x16x32_bf16 v[90:93], v[146:149], v[188:191], v[90:93]
	v_mfma_f32_16x16x32_bf16 v[90:93], v[150:153], v[202:205], v[90:93]
	v_mfma_f32_16x16x32_bf16 v[86:89], v[154:157], v[188:191], v[86:89]
	v_mfma_f32_16x16x32_bf16 v[86:89], v[158:161], v[202:205], v[86:89]
	v_mfma_f32_16x16x32_bf16 v[66:69], v[154:157], v[206:209], v[66:69]
	v_mfma_f32_16x16x32_bf16 v[66:69], v[158:161], v[210:213], v[66:69]
	v_mfma_f32_16x16x32_bf16 v[70:73], v[146:149], v[206:209], v[70:73]
	v_mfma_f32_16x16x32_bf16 v[70:73], v[150:153], v[210:213], v[70:73]
	v_mfma_f32_16x16x32_bf16 v[78:81], v[114:117], v[206:209], v[78:81]
	v_mfma_f32_16x16x32_bf16 v[78:81], v[134:137], v[210:213], v[78:81]
	v_mfma_f32_16x16x32_bf16 v[82:85], v[74:77], v[206:209], v[82:85]
	v_mfma_f32_16x16x32_bf16 v[82:85], v[94:97], v[210:213], v[82:85]
	s_barrier
; #define PG8_STAGE(bufoff, gbase, voff) do { _Pragma("unroll") for (int _i = 0; _i < 2; ++_i) { \
;         const unsigned _m0 = ldsb + (unsigned)((bufoff) + _i * 8192); const char* _gb = (const char*)(gbase); \
;         asm volatile("s_mov_b32 m0, %0\n\ts_nop 0\n\tglobal_load_lds_dwordx4 %1, %2" :: "s"(_m0), "v"((voff)[_i]), "s"(_gb) : "m0", "memory"); } } while (0)
; #define PG8_LDA(dst, b, h) do { _Pragma("unroll") for (int m = 0; m < 4; ++m) _Pragma("unroll") for (int k = 0; k < 2; ++k) dst[m][k] = *(const LAS bf16x8*)(lds + PG8_SA(b, h) + aoff + m * 2048 + k * 1024); } while (0)
; #define PG8_LDB(dst, b, h) do { _Pragma("unroll") for (int n = 0; n < 2; ++n) _Pragma("unroll") for (int k = 0; k < 2; ++k) dst[n][k] = *(const LAS bf16x8*)(lds + PG8_SB(b, h) + boff + n * 2048 + k * 1024); } while (0)
; #define PG8_MMA(ai, bj, At, Bt) do { __builtin_amdgcn_s_setprio(1); _Pragma("unroll") for (int m = 0; m < 4; ++m) _Pragma("unroll") for (int n = 0; n < 2; ++n) _Pragma("unroll") for (int k = 0; k < 2; ++k) \
;         acc[ai][bj][m][n] = __builtin_amdgcn_mfma_f32_16x16x32_bf16(Bt[n][k], At[m][k], acc[ai][bj][m][n], 0, 0, 0); __builtin_amdgcn_s_setprio(0); } while (0)
; #define PG8_WAIT_V(n) asm volatile("s_waitcnt vmcnt(" #n ")" ::: "memory")
; #define PG8_WAIT_L(n) asm volatile("s_waitcnt lgkmcnt(" #n ")" ::: "memory")
; template <class Epi, bool ALIGN_EPI>
; __device__ __forceinline__ void gemm_phase(LAS unsigned char* lds, const Gemm g, const StaticOrder& S, const Epi& E) {
;     ...
;         const char* nA = has_next ? (const char*)g.A + (size_t)nxt.pm * tstepA + (size_t)nxt.pn * g.a_pn_off * 2 + (size_t)(nxt.pm >> 4) * g.a_adj : cA; const char* nB = has_next ? (const char*)g.Bt + (size_t)nxt.pn * tstepB : cB;
;     ...
;             PG8_WAIT_V(8); PG8_WAIT_L(0); PG8_BAR; PG8_MMA(1, 0, At, B0); PG8_MMA(1, 1, At, B1); PG8_BAR; PG8_SCHED;
;             PG8_LDB(B0, 1, 0); PG8_LDB(B1, 1, 1); PG8_SCHED; PG8_LDA(At, 1, 0); PG8_STAGE(PG8_SA(0, 1), a2 + hstepA, voffA);
;             PG8_WAIT_V(8); PG8_WAIT_L(0); PG8_BAR; PG8_MMA(0, 0, At, B0); PG8_MMA(0, 1, At, B1); PG8_BAR; PG8_SCHED;
;             PG8_LDA(At, 1, 1); PG8_STAGE(PG8_SB(1, 0), b3, voffB); PG8_STAGE(PG8_SB(1, 1), b3 + hstepB, voffB); PG8_STAGE(PG8_SA(1, 0), a3, voffA);
;             PG8_WAIT_V(8); PG8_WAIT_L(0); PG8_BAR; PG8_MMA(1, 0, At, B0); PG8_MMA(1, 1, At, B1); PG8_BAR; PG8_SCHED;
	s_setprio 0
	ds_read_b128 v[162:165], v186 offset:49152
	ds_read_b128 v[166:169], v186 offset:50176
	ds_read_b128 v[170:173], v186 offset:51200
	ds_read_b128 v[174:177], v186 offset:52224
	ds_read_b128 v[188:191], v186 offset:53248
	ds_read_b128 v[202:205], v186 offset:54272
	ds_read_b128 v[206:209], v186 offset:55296
	ds_read_b128 v[210:213], v186 offset:56320
	s_add_u32 s30, s58, 0x80
	s_addc_u32 s31, s59, 0
	s_mov_b32 m0, s94
	s_nop 0
	global_load_lds_dwordx4 v180, s[30:31]
	s_nop 0
	s_mov_b32 m0, s95
	s_nop 0
	global_load_lds_dwordx4 v182, s[30:31]
	s_add_u32 s30, s58, 0x40080
	s_addc_u32 s31, s59, 0
	s_mov_b32 m0, s17
	s_nop 0
	global_load_lds_dwordx4 v180, s[30:31]
	s_nop 0
	s_mov_b32 m0, s53
	s_nop 0
	global_load_lds_dwordx4 v182, s[30:31]
	s_nop 0
	s_mov_b32 m0, s96
	s_nop 0
	global_load_lds_dwordx4 v0, s[56:57]
	s_nop 0
	s_mov_b32 m0, s97
	s_nop 0
	global_load_lds_dwordx4 v181, s[56:57]
	s_add_i32 s36, s4, s90
	s_ashr_i32 s37, s36, 31
	s_lshl_b64 s[4:5], s[36:37], 19
	s_add_u32 s38, s18, s4
	s_addc_u32 s39, s19, s5
	s_and_b64 s[4:5], s[8:9], exec
	s_cselect_b32 s4, s39, s59
	s_cselect_b32 s5, s38, s58
	s_ashr_i32 s35, s34, 31
	s_lshl_b64 vcc, s[34:35], 19
	s_add_u32 s90, s1, vcc_lo
	s_addc_u32 s91, s14, vcc_hi
	s_and_b64 vcc, s[8:9], exec
	s_cselect_b32 s35, s91, s57
	s_cselect_b32 s37, s90, s56
	s_waitcnt vmcnt(8)
	s_waitcnt lgkmcnt(0)
	s_setprio 1
	s_barrier
	v_mfma_f32_16x16x32_bf16 v[62:65], v[74:77], v[162:165], v[62:65]
	v_mfma_f32_16x16x32_bf16 v[62:65], v[94:97], v[166:169], v[62:65]
	v_mfma_f32_16x16x32_bf16 v[58:61], v[114:117], v[162:165], v[58:61]
	v_mfma_f32_16x16x32_bf16 v[58:61], v[134:137], v[166:169], v[58:61]
	v_mfma_f32_16x16x32_bf16 v[54:57], v[146:149], v[162:165], v[54:57]
	v_mfma_f32_16x16x32_bf16 v[54:57], v[150:153], v[166:169], v[54:57]
	v_mfma_f32_16x16x32_bf16 v[50:53], v[154:157], v[162:165], v[50:53]
	v_mfma_f32_16x16x32_bf16 v[50:53], v[158:161], v[166:169], v[50:53]
	v_mfma_f32_16x16x32_bf16 v[34:37], v[154:157], v[170:173], v[34:37]
	v_mfma_f32_16x16x32_bf16 v[34:37], v[158:161], v[174:177], v[34:37]
	v_mfma_f32_16x16x32_bf16 v[38:41], v[146:149], v[170:173], v[38:41]
	v_mfma_f32_16x16x32_bf16 v[38:41], v[150:153], v[174:177], v[38:41]
	v_mfma_f32_16x16x32_bf16 v[42:45], v[114:117], v[170:173], v[42:45]
	v_mfma_f32_16x16x32_bf16 v[42:45], v[134:137], v[174:177], v[42:45]
	v_mfma_f32_16x16x32_bf16 v[46:49], v[74:77], v[170:173], v[46:49]
	v_mfma_f32_16x16x32_bf16 v[46:49], v[94:97], v[174:177], v[46:49]
	v_mfma_f32_16x16x32_bf16 v[30:33], v[74:77], v[188:191], v[30:33]
	v_mfma_f32_16x16x32_bf16 v[30:33], v[94:97], v[202:205], v[30:33]
	v_mfma_f32_16x16x32_bf16 v[26:29], v[114:117], v[188:191], v[26:29]
	v_mfma_f32_16x16x32_bf16 v[26:29], v[134:137], v[202:205], v[26:29]
	v_mfma_f32_16x16x32_bf16 v[22:25], v[146:149], v[188:191], v[22:25]
	v_mfma_f32_16x16x32_bf16 v[22:25], v[150:153], v[202:205], v[22:25]
	v_mfma_f32_16x16x32_bf16 v[18:21], v[154:157], v[188:191], v[18:21]
	v_mfma_f32_16x16x32_bf16 v[18:21], v[158:161], v[202:205], v[18:21]
	v_mfma_f32_16x16x32_bf16 v[2:5], v[154:157], v[206:209], v[2:5]
	v_mfma_f32_16x16x32_bf16 v[2:5], v[158:161], v[210:213], v[2:5]
	v_mfma_f32_16x16x32_bf16 v[6:9], v[146:149], v[206:209], v[6:9]
	v_mfma_f32_16x16x32_bf16 v[6:9], v[150:153], v[210:213], v[6:9]
	v_mfma_f32_16x16x32_bf16 v[10:13], v[114:117], v[206:209], v[10:13]
	v_mfma_f32_16x16x32_bf16 v[10:13], v[134:137], v[210:213], v[10:13]
	v_mfma_f32_16x16x32_bf16 v[14:17], v[74:77], v[206:209], v[14:17]
	v_mfma_f32_16x16x32_bf16 v[14:17], v[94:97], v[210:213], v[14:17]
	s_barrier
	s_setprio 0
	s_add_i32 s50, s50, 2
	s_add_u32 s41, s41, 0x100
	s_addc_u32 s49, s49, 0
	s_add_u32 s92, s92, 0x100
	s_addc_u32 s93, s93, 0
	s_cmp_gt_u32 s50, 13
